# relax_pa
# speedup vs baseline: 1.0009x; 1.0009x over previous
; #define PG8_STAGE(bufoff, gbase, voff) do { _Pragma("unroll") for (int _i = 0; _i < 2; ++_i) \
;         __builtin_amdgcn_global_load_lds((const unsigned*)((const char*)(gbase) + (voff)[_i]), (LAS unsigned*)(lds + (bufoff) + ldsw + _i * 8192), 16, 0, 0); } while (0)
; #define PG8_WAIT_V(n) asm volatile("s_waitcnt vmcnt(" #n ")" ::: "memory")
; #define PG8_BAR __builtin_amdgcn_s_barrier()
; template <class Epi, class Sched>
; __device__ __forceinline__ void gemm_phase(LAS unsigned char* lds, const Sched& S, const Epi& E, bool natural = false) {
;     ...
;     PG8_STAGE(PG8_SB(0, 0), cB, voffB0); PG8_STAGE(PG8_SB(0, 1), cB, voffB1); PG8_STAGE(PG8_SA(0, 0), cA, voffA); PG8_STAGE(PG8_SA(0, 1), cA + hstep, voffA);
;     if (wr == 1) PG8_BAR;
;     PG8_WAIT_V(2); PG8_BAR;
;     PG8_STAGE(PG8_SB(1, 0), cB + kstep, voffB0); PG8_STAGE(PG8_SA(1, 0), cA + kstep, voffA); PG8_STAGE(PG8_SB(1, 1), cB + kstep, voffB1);
;     PG8_WAIT_V(6); PG8_BAR;
;     __device__ __forceinline__ void operator()(AccT& acc, const Unit& u, int wr, int wc, int fr, int fq) const {
;     ...
;         bf16_t* const QA = (bf16_t*)(ws + WS_QA); bf16_t* const KA = (bf16_t*)(ws + WS_KA); bf16_t* const QB = (bf16_t*)(ws + WS_QB); bf16_t* const KB = (bf16_t*)(ws + WS_KB);
;         bf16_t* const VBT = (bf16_t*)(ws + WS_VBT); bf16_t* const ZA = (bf16_t*)(ws + WS_ZA); bf16_t* const ZB = (bf16_t*)(ws + WS_ZB); bf16_t* const VAT = (bf16_t*)(ws + WS_VAT);
;         bf16_t* const GB = GA + (size_t)T * 1024;
.LBB0_166:
	s_waitcnt vmcnt(0)
	v_and_b32_e32 v13, 15, v190
	v_lshlrev_b32_e32 v12, 1, v152
	v_lshlrev_b32_e32 v14, 2, v190
	s_and_b32 s5, s0, 3
	v_lshl_or_b32 v153, s1, 6, v13
	v_lshl_or_b32 v13, v13, 6, v12
	s_lshl_b32 s0, s1, 13
	v_and_b32_e32 v14, 32, v14
	v_bitop3_b32 v15, v13, s0, v14 bitop3:0xde
	v_lshlrev_b32_e32 v13, 6, v190
	s_movk_i32 s0, 0x3c0
	s_lshl_b32 s14, s5, 12
	v_and_or_b32 v13, v13, s0, v12
	s_mov_b64 s[12:13], 0x80
	s_add_u32 s0, s42, 0x80
	s_addc_u32 s1, s43, 0
	s_add_i32 m0, s39, 0x18000
	v_lshl_add_u64 v[4:5], v[4:5], 0, s[12:13]
	s_waitcnt vmcnt(2)
	s_barrier
	global_load_lds_dwordx4 v[4:5], off
	v_lshl_add_u64 v[0:1], v[0:1], 0, s[12:13]
	s_add_i32 m0, s39, 0x1a000
	s_add_i32 s51, s39, 0x8000
	global_load_lds_dwordx4 v[0:1], off
	v_lshl_add_u64 v[0:1], v[2:3], 0, s[12:13]
	s_mov_b32 m0, s51
	s_add_i32 s52, s39, 0xa000
	global_load_lds_dwordx4 v[0:1], off
	v_lshl_add_u64 v[0:1], v[6:7], 0, s[12:13]
	s_mov_b32 m0, s52
	v_bitop3_b32 v192, s14, v13, v14 bitop3:0xf6
	global_load_lds_dwordx4 v[0:1], off
	s_add_i32 m0, s39, 0x1c000
	v_lshl_add_u64 v[0:1], s[0:1], 0, v[158:159]
	global_load_lds_dwordx4 v[0:1], off
	v_lshl_add_u64 v[0:1], s[0:1], 0, v[164:165]
	s_add_i32 m0, s39, 0x1e000
	s_cmpk_lt_u32 s4, 0x100
	global_load_lds_dwordx4 v[0:1], off
	s_cselect_b64 s[14:15], -1, 0
	s_lshl_b32 s53, s5, 6
	s_cmp_gt_u32 s5, 1
	s_waitcnt lgkmcnt(0)
	s_cselect_b64 s[80:81], -1, 0
	v_and_b32_e32 v0, 7, v190
	s_or_b32 s54, s53, 0xfffffc00
	s_or_b32 s55, s53, 0xfffffe00
	s_ashr_i32 s56, s50, 31
	s_ashr_i32 s57, s2, 31
	v_lshl_or_b32 v1, s5, 5, v152
	v_or_b32_e32 v194, s53, v152
	s_add_u32 s82, s64, 0x16100000
	v_or_b32_e32 v195, 0xfffffa80, v1
	v_lshlrev_b32_e32 v0, 1, v0
	v_mov_b32_e32 v1, v167
	v_add_u32_e32 v166, 0xffffff80, v194
	s_addc_u32 s83, s65, 0
	v_lshl_add_u64 v[0:1], s[64:65], 0, v[0:1]
	s_add_u32 s96, s62, 0x6000000
	v_lshl_add_u64 v[0:1], v[166:167], 4, v[0:1]
	s_mov_b64 s[0:1], 0x19d00000
	s_addc_u32 s97, s63, 0
	v_lshl_add_u64 v[168:169], v[0:1], 0, s[0:1]
	s_lshl_b32 s0, s5, 7
	s_add_u32 s0, s64, s0
	s_addc_u32 s1, s65, 0
	v_mov_b32_e32 v13, v167
	v_lshl_add_u64 v[0:1], s[0:1], 0, v[12:13]
	s_mov_b64 s[0:1], 0x19100000
	v_lshl_add_u64 v[170:171], v[0:1], 0, s[0:1]
	v_lshl_add_u64 v[0:1], s[64:65], 0, v[12:13]
	s_mov_b64 s[0:1], 0xd100000
	v_lshl_add_u64 v[172:173], v[0:1], 0, s[0:1]
	s_mov_b64 s[0:1], 0xa100000
	v_lshl_add_u64 v[174:175], v[0:1], 0, s[0:1]
	s_mov_b64 s[0:1], 0x7100000
	v_lshl_add_u64 v[176:177], v[0:1], 0, s[0:1]
	v_lshlrev_b32_e32 v0, 8, v190
	v_and_b32_e32 v0, 0x38000, v0
	v_lshlrev_b32_e32 v1, 11, v10
	v_or3_b32 v0, v8, v0, v1
	v_add_u32_e32 v178, v0, v9
	v_lshlrev_b32_e32 v0, 4, v11
	v_and_b32_e32 v0, 0x78000, v0
	s_waitcnt vmcnt(0)
	v_or3_b32 v0, v8, v0, v1
	v_add_u32_e32 v180, v0, v9
	s_add_i32 s59, 0, 0x10000
	s_add_i32 s60, 0, 0x14000
	v_mbcnt_lo_u32_b32 v0, -1, 0
	v_add_u32_e32 v193, 0xffffed00, v153
	v_mov_b32_e32 v179, v167
	v_mov_b32_e32 v181, v167
	v_mov_b64_e32 v[182:183], 0xfc0
	v_mov_b64_e32 v[184:185], 0xfbf
	s_movk_i32 s58, 0x1f9
	v_add_u32_e32 v196, s59, v192
	v_add_u32_e32 v197, s60, v192
	v_add_u32_e32 v198, 0, v15
	s_mov_b32 s24, 0xbfb8aa3b
	s_mov_b64 s[26:27], 0x100ff200
	v_mov_b32_e32 v199, 0x358637bd
	s_movk_i32 s61, 0xfdf
	s_movk_i32 s68, 0xfef
	s_movk_i32 s69, 0xfff
	s_mov_b32 s28, 0x3e38aa3b
	v_mbcnt_hi_u32_b32 v200, -1, v0
	s_mov_b32 s70, 0
	s_barrier
	s_branch .LBB0_169

; #define PG8_STAGE(bufoff, gbase, voff) do { _Pragma("unroll") for (int _i = 0; _i < 2; ++_i) \
;         __builtin_amdgcn_global_load_lds((const unsigned*)((const char*)(gbase) + (voff)[_i]), (LAS unsigned*)(lds + (bufoff) + ldsw + _i * 8192), 16, 0, 0); } while (0)
; #define PG8_LDA(dst, b, h) do { _Pragma("unroll") for (int m = 0; m < 4; ++m) _Pragma("unroll") for (int k = 0; k < 2; ++k) dst[m][k] = *(const LAS bf16x8*)(lds + PG8_SA(b, h) + aoff + m * 2048 + k * 1024); } while (0)
; #define PG8_LDB(dst, b, h) do { _Pragma("unroll") for (int n = 0; n < 2; ++n) _Pragma("unroll") for (int k = 0; k < 2; ++k) dst[n][k] = *(const LAS bf16x8*)(lds + PG8_SB(b, h) + boff + n * 2048 + k * 1024); } while (0)
; #define PG8_MMA(ai, bj, At, Bt) do { __builtin_amdgcn_s_setprio(1); _Pragma("unroll") for (int m = 0; m < 4; ++m) _Pragma("unroll") for (int n = 0; n < 2; ++n) _Pragma("unroll") for (int k = 0; k < 2; ++k) \
;         acc[ai][bj][m][n] = __builtin_amdgcn_mfma_f32_16x16x32_bf16(Bt[n][k], At[m][k], acc[ai][bj][m][n], 0, 0, 0); __builtin_amdgcn_s_setprio(0); } while (0)
; #define PG8_WAIT_V(n) asm volatile("s_waitcnt vmcnt(" #n ")" ::: "memory")
; #define PG8_WAIT_L(n) asm volatile("s_waitcnt lgkmcnt(" #n ")" ::: "memory")
; #define PG8_BAR __builtin_amdgcn_s_barrier()
; #define PG8_SCHED __builtin_amdgcn_sched_barrier(0)
; template <class Epi, class Sched>
; __device__ __forceinline__ void gemm_phase(LAS unsigned char* lds, const Sched& S, const Epi& E, bool natural = false) {
;     ...
;             PG8_LDB(B0, 0, 0); PG8_LDB(B1, 0, 1); PG8_SCHED; PG8_LDA(At, 0, 0); PG8_STAGE(PG8_SA(1, 1), a1 + hstep, voffA);
;             PG8_WAIT_V(8); PG8_WAIT_L(0); PG8_BAR; PG8_MMA(0, 0, At, B0); PG8_MMA(0, 1, At, B1); PG8_BAR; PG8_SCHED;
;             PG8_LDA(At, 0, 1); PG8_STAGE(PG8_SB(0, 0), b2, voffB0); PG8_STAGE(PG8_SB(0, 1), b2, voffB1); PG8_STAGE(PG8_SA(0, 0), a2, voffA);
;             PG8_WAIT_V(8); PG8_WAIT_L(0); PG8_BAR; PG8_MMA(1, 0, At, B0); PG8_MMA(1, 1, At, B1); PG8_BAR; PG8_SCHED;
.LBB0_174:
	ds_read_b128 v[128:131], v196
	ds_read_b128 v[132:135], v196 offset:1024
	ds_read_b128 v[136:139], v196 offset:2048
	ds_read_b128 v[140:143], v196 offset:3072
	ds_read_b128 v[144:147], v197
	ds_read_b128 v[148:151], v197 offset:1024
	ds_read_b128 v[186:189], v197 offset:2048
	ds_read_b128 v[202:205], v197 offset:3072
	s_add_u32 s42, s40, 0xfffc0080
	s_addc_u32 s43, s41, -1
	s_cmp_eq_u32 s71, 12
	s_cselect_b32 s45, s1, s43
	s_cselect_b32 s44, s0, s42
	s_cselect_b32 s43, s37, s35
	s_cselect_b32 s42, s36, s31
	v_lshl_add_u64 v[238:239], s[40:41], 0, v[178:179]
	s_add_i32 m0, s39, 0xc000
	ds_read_b128 v[206:209], v198
	ds_read_b128 v[210:213], v198 offset:1024
	ds_read_b128 v[214:217], v198 offset:2048
	ds_read_b128 v[218:221], v198 offset:3072
	ds_read_b128 v[222:225], v198 offset:4096
	ds_read_b128 v[226:229], v198 offset:5120
	ds_read_b128 v[230:233], v198 offset:6144
	ds_read_b128 v[234:237], v198 offset:7168
	global_load_lds_dwordx4 v[238:239], off
	v_lshl_add_u64 v[238:239], s[40:41], 0, v[180:181]
	s_add_i32 m0, s39, 0xe000
	s_nop 0
	global_load_lds_dwordx4 v[238:239], off
	s_cmp_lg_u32 s71, -2
	s_cbranch_scc1 .Lw8_pa0
	s_waitcnt vmcnt(24)
	s_branch .Lwd_pa0
.Lw8_pa0:
	s_waitcnt vmcnt(8)
.Lwd_pa0:
	s_waitcnt lgkmcnt(0)
	s_barrier
	s_setprio 1
	s_waitcnt lgkmcnt(0)
	v_mfma_f32_16x16x32_bf16 v[124:127], v[128:131], v[206:209], v[124:127]
	v_mfma_f32_16x16x32_bf16 v[120:123], v[136:139], v[206:209], v[120:123]
	v_mfma_f32_16x16x32_bf16 v[108:111], v[128:131], v[214:217], v[108:111]
	v_mfma_f32_16x16x32_bf16 v[104:107], v[136:139], v[214:217], v[104:107]
	v_mfma_f32_16x16x32_bf16 v[92:95], v[128:131], v[222:225], v[92:95]
	v_mfma_f32_16x16x32_bf16 v[88:91], v[136:139], v[222:225], v[88:91]
	v_mfma_f32_16x16x32_bf16 v[76:79], v[128:131], v[230:233], v[76:79]
	v_mfma_f32_16x16x32_bf16 v[72:75], v[136:139], v[230:233], v[72:75]
	v_mfma_f32_16x16x32_bf16 v[124:127], v[132:135], v[210:213], v[124:127]
	v_mfma_f32_16x16x32_bf16 v[120:123], v[140:143], v[210:213], v[120:123]
	v_mfma_f32_16x16x32_bf16 v[108:111], v[132:135], v[218:221], v[108:111]
	v_mfma_f32_16x16x32_bf16 v[104:107], v[140:143], v[218:221], v[104:107]
	v_mfma_f32_16x16x32_bf16 v[92:95], v[132:135], v[226:229], v[92:95]
	v_mfma_f32_16x16x32_bf16 v[88:91], v[140:143], v[226:229], v[88:91]
	v_mfma_f32_16x16x32_bf16 v[76:79], v[132:135], v[234:237], v[76:79]
	v_mfma_f32_16x16x32_bf16 v[72:75], v[140:143], v[234:237], v[72:75]
	s_setprio 0
	s_setprio 1
	v_mfma_f32_16x16x32_bf16 v[116:119], v[144:147], v[206:209], v[116:119]
	v_mfma_f32_16x16x32_bf16 v[112:115], v[186:189], v[206:209], v[112:115]
	v_mfma_f32_16x16x32_bf16 v[100:103], v[144:147], v[214:217], v[100:103]
	v_mfma_f32_16x16x32_bf16 v[96:99], v[186:189], v[214:217], v[96:99]
	v_mfma_f32_16x16x32_bf16 v[84:87], v[144:147], v[222:225], v[84:87]
	v_mfma_f32_16x16x32_bf16 v[80:83], v[186:189], v[222:225], v[80:83]
	v_mfma_f32_16x16x32_bf16 v[68:71], v[144:147], v[230:233], v[68:71]
	v_mfma_f32_16x16x32_bf16 v[64:67], v[186:189], v[230:233], v[64:67]
	v_mfma_f32_16x16x32_bf16 v[116:119], v[148:151], v[210:213], v[116:119]
	v_mfma_f32_16x16x32_bf16 v[112:115], v[202:205], v[210:213], v[112:115]
	v_mfma_f32_16x16x32_bf16 v[100:103], v[148:151], v[218:221], v[100:103]
	v_mfma_f32_16x16x32_bf16 v[96:99], v[202:205], v[218:221], v[96:99]
	v_mfma_f32_16x16x32_bf16 v[84:87], v[148:151], v[226:229], v[84:87]
	v_mfma_f32_16x16x32_bf16 v[80:83], v[202:205], v[226:229], v[80:83]
	v_mfma_f32_16x16x32_bf16 v[68:71], v[148:151], v[234:237], v[68:71]
	v_mfma_f32_16x16x32_bf16 v[64:67], v[202:205], v[234:237], v[64:67]
	s_setprio 0
	s_barrier
	s_add_i32 s72, s59, s33
	v_lshl_add_u64 v[238:239], s[42:43], 0, v[156:157]
	s_mov_b32 m0, s72
	ds_read_b128 v[206:209], v198 offset:16384
	ds_read_b128 v[210:213], v198 offset:17408
	ds_read_b128 v[214:217], v198 offset:18432
	ds_read_b128 v[218:221], v198 offset:19456
	ds_read_b128 v[222:225], v198 offset:20480
	ds_read_b128 v[226:229], v198 offset:21504
	ds_read_b128 v[230:233], v198 offset:22528
	ds_read_b128 v[234:237], v198 offset:23552
	global_load_lds_dwordx4 v[238:239], off
	v_lshl_add_u64 v[240:241], s[42:43], 0, v[162:163]
	s_add_i32 m0, s72, 0x2000
	s_add_i32 s72, s60, s33
	global_load_lds_dwordx4 v[240:241], off
	v_lshl_add_u64 v[242:243], s[42:43], 0, v[158:159]
	s_mov_b32 m0, s72
	v_lshl_add_u64 v[244:245], s[44:45], 0, v[160:161]
	global_load_lds_dwordx4 v[242:243], off
	v_lshl_add_u64 v[242:243], s[42:43], 0, v[164:165]
	s_add_i32 m0, s72, 0x2000
	s_nop 0
	global_load_lds_dwordx4 v[242:243], off
	v_lshl_add_u64 v[242:243], s[44:45], 0, v[154:155]
	s_mov_b32 m0, s39
	s_nop 0
	global_load_lds_dwordx4 v[242:243], off
	s_mov_b32 m0, s46
	s_nop 0
	global_load_lds_dwordx4 v[244:245], off
	s_cmp_lg_u32 s71, -2
	s_cbranch_scc1 .Lw8_pa1
	s_waitcnt vmcnt(24)
	s_branch .Lwd_pa1

; #define PG8_STAGE(bufoff, gbase, voff) do { _Pragma("unroll") for (int _i = 0; _i < 2; ++_i) \
;         __builtin_amdgcn_global_load_lds((const unsigned*)((const char*)(gbase) + (voff)[_i]), (LAS unsigned*)(lds + (bufoff) + ldsw + _i * 8192), 16, 0, 0); } while (0)
; #define PG8_LDA(dst, b, h) do { _Pragma("unroll") for (int m = 0; m < 4; ++m) _Pragma("unroll") for (int k = 0; k < 2; ++k) dst[m][k] = *(const LAS bf16x8*)(lds + PG8_SA(b, h) + aoff + m * 2048 + k * 1024); } while (0)
; #define PG8_LDB(dst, b, h) do { _Pragma("unroll") for (int n = 0; n < 2; ++n) _Pragma("unroll") for (int k = 0; k < 2; ++k) dst[n][k] = *(const LAS bf16x8*)(lds + PG8_SB(b, h) + boff + n * 2048 + k * 1024); } while (0)
; #define PG8_MMA(ai, bj, At, Bt) do { __builtin_amdgcn_s_setprio(1); _Pragma("unroll") for (int m = 0; m < 4; ++m) _Pragma("unroll") for (int n = 0; n < 2; ++n) _Pragma("unroll") for (int k = 0; k < 2; ++k) \
;         acc[ai][bj][m][n] = __builtin_amdgcn_mfma_f32_16x16x32_bf16(Bt[n][k], At[m][k], acc[ai][bj][m][n], 0, 0, 0); __builtin_amdgcn_s_setprio(0); } while (0)
; #define PG8_WAIT_V(n) asm volatile("s_waitcnt vmcnt(" #n ")" ::: "memory")
; #define PG8_WAIT_L(n) asm volatile("s_waitcnt lgkmcnt(" #n ")" ::: "memory")
; #define PG8_BAR __builtin_amdgcn_s_barrier()
; #define PG8_SCHED __builtin_amdgcn_sched_barrier(0)
; template <class Epi, class Sched>
; __device__ __forceinline__ void gemm_phase(LAS unsigned char* lds, const Sched& S, const Epi& E, bool natural = false) {
;     ...
;             PG8_WAIT_V(8); PG8_WAIT_L(0); PG8_BAR; PG8_MMA(1, 0, At, B0); PG8_MMA(1, 1, At, B1); PG8_BAR; PG8_SCHED;
;             PG8_LDB(B0, 1, 0); PG8_LDB(B1, 1, 1); PG8_SCHED; PG8_LDA(At, 1, 0); PG8_STAGE(PG8_SA(0, 1), a2 + hstep, voffA);
;             PG8_WAIT_V(8); PG8_WAIT_L(0); PG8_BAR; PG8_MMA(0, 0, At, B0); PG8_MMA(0, 1, At, B1); PG8_BAR; PG8_SCHED;
.Lwd_pa1:
	s_waitcnt lgkmcnt(0)
	s_barrier
	s_setprio 1
	s_waitcnt lgkmcnt(0)
	v_mfma_f32_16x16x32_bf16 v[60:63], v[128:131], v[206:209], v[60:63]
	v_mfma_f32_16x16x32_bf16 v[56:59], v[136:139], v[206:209], v[56:59]
	v_mfma_f32_16x16x32_bf16 v[44:47], v[128:131], v[214:217], v[44:47]
	v_mfma_f32_16x16x32_bf16 v[40:43], v[136:139], v[214:217], v[40:43]
	v_mfma_f32_16x16x32_bf16 v[28:31], v[128:131], v[222:225], v[28:31]
	v_mfma_f32_16x16x32_bf16 v[24:27], v[136:139], v[222:225], v[24:27]
	v_mfma_f32_16x16x32_bf16 v[12:15], v[128:131], v[230:233], v[12:15]
	v_mfma_f32_16x16x32_bf16 v[8:11], v[136:139], v[230:233], v[8:11]
	v_mfma_f32_16x16x32_bf16 v[60:63], v[132:135], v[210:213], v[60:63]
	v_mfma_f32_16x16x32_bf16 v[56:59], v[140:143], v[210:213], v[56:59]
	v_mfma_f32_16x16x32_bf16 v[44:47], v[132:135], v[218:221], v[44:47]
	v_mfma_f32_16x16x32_bf16 v[40:43], v[140:143], v[218:221], v[40:43]
	v_mfma_f32_16x16x32_bf16 v[28:31], v[132:135], v[226:229], v[28:31]
	v_mfma_f32_16x16x32_bf16 v[24:27], v[140:143], v[226:229], v[24:27]
	v_mfma_f32_16x16x32_bf16 v[12:15], v[132:135], v[234:237], v[12:15]
	v_mfma_f32_16x16x32_bf16 v[8:11], v[140:143], v[234:237], v[8:11]
	s_setprio 0
	s_setprio 1
	v_mfma_f32_16x16x32_bf16 v[52:55], v[144:147], v[206:209], v[52:55]
	v_mfma_f32_16x16x32_bf16 v[48:51], v[186:189], v[206:209], v[48:51]
	v_mfma_f32_16x16x32_bf16 v[36:39], v[144:147], v[214:217], v[36:39]
	v_mfma_f32_16x16x32_bf16 v[32:35], v[186:189], v[214:217], v[32:35]
	v_mfma_f32_16x16x32_bf16 v[20:23], v[144:147], v[222:225], v[20:23]
	v_mfma_f32_16x16x32_bf16 v[16:19], v[186:189], v[222:225], v[16:19]
	v_mfma_f32_16x16x32_bf16 v[4:7], v[144:147], v[230:233], v[4:7]
	v_mfma_f32_16x16x32_bf16 v[0:3], v[186:189], v[230:233], v[0:3]
	v_mfma_f32_16x16x32_bf16 v[52:55], v[148:151], v[210:213], v[52:55]
	v_mfma_f32_16x16x32_bf16 v[48:51], v[202:205], v[210:213], v[48:51]
	v_mfma_f32_16x16x32_bf16 v[36:39], v[148:151], v[218:221], v[36:39]
	v_mfma_f32_16x16x32_bf16 v[32:35], v[202:205], v[218:221], v[32:35]
	v_mfma_f32_16x16x32_bf16 v[20:23], v[148:151], v[226:229], v[20:23]
	v_mfma_f32_16x16x32_bf16 v[16:19], v[202:205], v[226:229], v[16:19]
	v_mfma_f32_16x16x32_bf16 v[4:7], v[148:151], v[234:237], v[4:7]
	v_mfma_f32_16x16x32_bf16 v[0:3], v[202:205], v[234:237], v[0:3]
	s_setprio 0
	s_barrier
	s_add_i32 s72, 0, 0x18000
	s_add_i32 s73, 0, 0x1c000
	v_add_u32_e32 v140, s72, v192
	v_add_u32_e32 v166, s73, v192
	ds_read_b128 v[128:131], v140
	ds_read_b128 v[132:135], v140 offset:1024
	ds_read_b128 v[136:139], v140 offset:2048
	ds_read_b128 v[140:143], v140 offset:3072
	ds_read_b128 v[144:147], v166
	ds_read_b128 v[148:151], v166 offset:1024
	ds_read_b128 v[186:189], v166 offset:2048
	ds_read_b128 v[202:205], v166 offset:3072
	s_add_u32 s44, s44, 0x40000
	s_addc_u32 s45, s45, 0
	s_mov_b32 m0, s47
	v_lshl_add_u64 v[246:247], s[44:45], 0, v[154:155]
	ds_read_b128 v[206:209], v198 offset:32768
	ds_read_b128 v[210:213], v198 offset:33792
	ds_read_b128 v[214:217], v198 offset:34816
	ds_read_b128 v[218:221], v198 offset:35840
	ds_read_b128 v[222:225], v198 offset:36864
	ds_read_b128 v[226:229], v198 offset:37888
	ds_read_b128 v[230:233], v198 offset:38912
	ds_read_b128 v[234:237], v198 offset:39936
	global_load_lds_dwordx4 v[246:247], off
	v_lshl_add_u64 v[246:247], s[44:45], 0, v[160:161]
	s_mov_b32 m0, s49
	s_nop 0
	global_load_lds_dwordx4 v[246:247], off
	s_waitcnt vmcnt(8)
	s_waitcnt lgkmcnt(0)
	s_barrier
	s_setprio 1
	s_waitcnt lgkmcnt(0)
	v_mfma_f32_16x16x32_bf16 v[124:127], v[128:131], v[206:209], v[124:127]
	v_mfma_f32_16x16x32_bf16 v[120:123], v[136:139], v[206:209], v[120:123]
	v_mfma_f32_16x16x32_bf16 v[108:111], v[128:131], v[214:217], v[108:111]
	v_mfma_f32_16x16x32_bf16 v[104:107], v[136:139], v[214:217], v[104:107]
	v_mfma_f32_16x16x32_bf16 v[92:95], v[128:131], v[222:225], v[92:95]
	v_mfma_f32_16x16x32_bf16 v[88:91], v[136:139], v[222:225], v[88:91]
	v_mfma_f32_16x16x32_bf16 v[76:79], v[128:131], v[230:233], v[76:79]
	v_mfma_f32_16x16x32_bf16 v[72:75], v[136:139], v[230:233], v[72:75]
	v_mfma_f32_16x16x32_bf16 v[124:127], v[132:135], v[210:213], v[124:127]
	v_mfma_f32_16x16x32_bf16 v[120:123], v[140:143], v[210:213], v[120:123]
	v_mfma_f32_16x16x32_bf16 v[108:111], v[132:135], v[218:221], v[108:111]
	v_mfma_f32_16x16x32_bf16 v[104:107], v[140:143], v[218:221], v[104:107]
	v_mfma_f32_16x16x32_bf16 v[92:95], v[132:135], v[226:229], v[92:95]
	v_mfma_f32_16x16x32_bf16 v[88:91], v[140:143], v[226:229], v[88:91]
	v_mfma_f32_16x16x32_bf16 v[76:79], v[132:135], v[234:237], v[76:79]
	v_mfma_f32_16x16x32_bf16 v[72:75], v[140:143], v[234:237], v[72:75]
	s_setprio 0
	s_setprio 1
	v_mfma_f32_16x16x32_bf16 v[116:119], v[144:147], v[206:209], v[116:119]
	v_mfma_f32_16x16x32_bf16 v[112:115], v[186:189], v[206:209], v[112:115]
	v_mfma_f32_16x16x32_bf16 v[100:103], v[144:147], v[214:217], v[100:103]
	v_mfma_f32_16x16x32_bf16 v[96:99], v[186:189], v[214:217], v[96:99]
	v_mfma_f32_16x16x32_bf16 v[84:87], v[144:147], v[222:225], v[84:87]
	v_mfma_f32_16x16x32_bf16 v[80:83], v[186:189], v[222:225], v[80:83]
	v_mfma_f32_16x16x32_bf16 v[68:71], v[144:147], v[230:233], v[68:71]
	v_mfma_f32_16x16x32_bf16 v[64:67], v[186:189], v[230:233], v[64:67]
	v_mfma_f32_16x16x32_bf16 v[116:119], v[148:151], v[210:213], v[116:119]
	v_mfma_f32_16x16x32_bf16 v[112:115], v[202:205], v[210:213], v[112:115]
	v_mfma_f32_16x16x32_bf16 v[100:103], v[148:151], v[218:221], v[100:103]
	v_mfma_f32_16x16x32_bf16 v[96:99], v[202:205], v[218:221], v[96:99]
	v_mfma_f32_16x16x32_bf16 v[84:87], v[148:151], v[226:229], v[84:87]
	v_mfma_f32_16x16x32_bf16 v[80:83], v[202:205], v[226:229], v[80:83]
	v_mfma_f32_16x16x32_bf16 v[68:71], v[148:151], v[234:237], v[68:71]
	v_mfma_f32_16x16x32_bf16 v[64:67], v[202:205], v[234:237], v[64:67]
	s_setprio 0
	s_barrier
; #define PG8_STAGE(bufoff, gbase, voff) do { _Pragma("unroll") for (int _i = 0; _i < 2; ++_i) \
;         __builtin_amdgcn_global_load_lds((const unsigned*)((const char*)(gbase) + (voff)[_i]), (LAS unsigned*)(lds + (bufoff) + ldsw + _i * 8192), 16, 0, 0); } while (0)
; #define PG8_LDA(dst, b, h) do { _Pragma("unroll") for (int m = 0; m < 4; ++m) _Pragma("unroll") for (int k = 0; k < 2; ++k) dst[m][k] = *(const LAS bf16x8*)(lds + PG8_SA(b, h) + aoff + m * 2048 + k * 1024); } while (0)
; #define PG8_MMA(ai, bj, At, Bt) do { __builtin_amdgcn_s_setprio(1); _Pragma("unroll") for (int m = 0; m < 4; ++m) _Pragma("unroll") for (int n = 0; n < 2; ++n) _Pragma("unroll") for (int k = 0; k < 2; ++k) \
;         acc[ai][bj][m][n] = __builtin_amdgcn_mfma_f32_16x16x32_bf16(Bt[n][k], At[m][k], acc[ai][bj][m][n], 0, 0, 0); __builtin_amdgcn_s_setprio(0); } while (0)
; #define PG8_WAIT_V(n) asm volatile("s_waitcnt vmcnt(" #n ")" ::: "memory")
; #define PG8_WAIT_L(n) asm volatile("s_waitcnt lgkmcnt(" #n ")" ::: "memory")
; #define PG8_BAR __builtin_amdgcn_s_barrier()
; #define PG8_SCHED __builtin_amdgcn_sched_barrier(0)
; template <class Epi, class Sched>
; __device__ __forceinline__ void gemm_phase(LAS unsigned char* lds, const Sched& S, const Epi& E, bool natural = false) {
;     ...
;             PG8_LDA(At, 1, 1); PG8_STAGE(PG8_SB(1, 0), b3, voffB0); PG8_STAGE(PG8_SB(1, 1), b3, voffB1); PG8_STAGE(PG8_SA(1, 0), a3, voffA);
;             PG8_WAIT_V(8); PG8_WAIT_L(0); PG8_BAR; PG8_MMA(1, 0, At, B0); PG8_MMA(1, 1, At, B1); PG8_BAR; PG8_SCHED;
;         }
;         if (wr == 0) PG8_BAR;
;         E(acc, cur, wr, wc, fr, fq);
	s_add_u32 s42, s42, 0x80
	s_addc_u32 s43, s43, 0
	s_add_i32 s44, s72, s33
	v_lshl_add_u64 v[238:239], v[238:239], 0, s[12:13]
	s_mov_b32 m0, s44
	ds_read_b128 v[206:209], v198 offset:49152
	ds_read_b128 v[210:213], v198 offset:50176
	ds_read_b128 v[214:217], v198 offset:51200
	ds_read_b128 v[218:221], v198 offset:52224
	ds_read_b128 v[222:225], v198 offset:53248
	ds_read_b128 v[226:229], v198 offset:54272
	ds_read_b128 v[230:233], v198 offset:55296
	ds_read_b128 v[234:237], v198 offset:56320
	global_load_lds_dwordx4 v[238:239], off
	v_lshl_add_u64 v[238:239], v[240:241], 0, s[12:13]
	s_add_i32 m0, s44, 0x2000
	s_add_i32 s44, s73, s33
	global_load_lds_dwordx4 v[238:239], off
	v_lshl_add_u64 v[238:239], s[42:43], 0, v[158:159]
	s_mov_b32 m0, s44
	s_nop 0
	global_load_lds_dwordx4 v[238:239], off
	v_lshl_add_u64 v[238:239], s[42:43], 0, v[164:165]
	s_add_i32 m0, s44, 0x2000
	s_nop 0
	global_load_lds_dwordx4 v[238:239], off
	v_lshl_add_u64 v[238:239], v[242:243], 0, s[12:13]
	s_mov_b32 m0, s51
	s_nop 0
	global_load_lds_dwordx4 v[238:239], off
	v_lshl_add_u64 v[238:239], v[244:245], 0, s[12:13]
	s_mov_b32 m0, s52
	s_nop 0
	global_load_lds_dwordx4 v[238:239], off
	s_waitcnt vmcnt(8)
	s_waitcnt lgkmcnt(0)
	s_barrier
	s_setprio 1
	s_waitcnt lgkmcnt(0)
	v_mfma_f32_16x16x32_bf16 v[60:63], v[128:131], v[206:209], v[60:63]
	v_mfma_f32_16x16x32_bf16 v[56:59], v[136:139], v[206:209], v[56:59]
	v_mfma_f32_16x16x32_bf16 v[44:47], v[128:131], v[214:217], v[44:47]
	v_mfma_f32_16x16x32_bf16 v[40:43], v[136:139], v[214:217], v[40:43]
	v_mfma_f32_16x16x32_bf16 v[28:31], v[128:131], v[222:225], v[28:31]
	v_mfma_f32_16x16x32_bf16 v[24:27], v[136:139], v[222:225], v[24:27]
	v_mfma_f32_16x16x32_bf16 v[12:15], v[128:131], v[230:233], v[12:15]
	v_mfma_f32_16x16x32_bf16 v[8:11], v[136:139], v[230:233], v[8:11]
	v_mfma_f32_16x16x32_bf16 v[60:63], v[132:135], v[210:213], v[60:63]
	v_mfma_f32_16x16x32_bf16 v[56:59], v[140:143], v[210:213], v[56:59]
	v_mfma_f32_16x16x32_bf16 v[44:47], v[132:135], v[218:221], v[44:47]
	v_mfma_f32_16x16x32_bf16 v[40:43], v[140:143], v[218:221], v[40:43]
	v_mfma_f32_16x16x32_bf16 v[28:31], v[132:135], v[226:229], v[28:31]
	v_mfma_f32_16x16x32_bf16 v[24:27], v[140:143], v[226:229], v[24:27]
	v_mfma_f32_16x16x32_bf16 v[12:15], v[132:135], v[234:237], v[12:15]
	v_mfma_f32_16x16x32_bf16 v[8:11], v[140:143], v[234:237], v[8:11]
	s_setprio 0
	s_setprio 1
	v_mfma_f32_16x16x32_bf16 v[52:55], v[144:147], v[206:209], v[52:55]
	v_mfma_f32_16x16x32_bf16 v[48:51], v[186:189], v[206:209], v[48:51]
	v_mfma_f32_16x16x32_bf16 v[36:39], v[144:147], v[214:217], v[36:39]
	v_mfma_f32_16x16x32_bf16 v[32:35], v[186:189], v[214:217], v[32:35]
	v_mfma_f32_16x16x32_bf16 v[20:23], v[144:147], v[222:225], v[20:23]
	v_mfma_f32_16x16x32_bf16 v[16:19], v[186:189], v[222:225], v[16:19]
	v_mfma_f32_16x16x32_bf16 v[4:7], v[144:147], v[230:233], v[4:7]
	v_mfma_f32_16x16x32_bf16 v[0:3], v[186:189], v[230:233], v[0:3]
	v_mfma_f32_16x16x32_bf16 v[52:55], v[148:151], v[210:213], v[52:55]
	v_mfma_f32_16x16x32_bf16 v[48:51], v[202:205], v[210:213], v[48:51]
	v_mfma_f32_16x16x32_bf16 v[36:39], v[148:151], v[218:221], v[36:39]
	v_mfma_f32_16x16x32_bf16 v[32:35], v[202:205], v[218:221], v[32:35]
	v_mfma_f32_16x16x32_bf16 v[20:23], v[148:151], v[226:229], v[20:23]
	v_mfma_f32_16x16x32_bf16 v[16:19], v[202:205], v[226:229], v[16:19]
	v_mfma_f32_16x16x32_bf16 v[4:7], v[148:151], v[234:237], v[4:7]
	v_mfma_f32_16x16x32_bf16 v[0:3], v[202:205], v[234:237], v[0:3]
	s_setprio 0
	s_barrier
	s_add_i32 s71, s71, 2
	s_add_u32 s40, s40, 0x100
	s_addc_u32 s41, s41, 0
	s_add_u32 s31, s31, 0x100
	s_addc_u32 s35, s35, 0
	s_cmp_gt_u32 s71, 13
	s_cbranch_scc0 .LBB0_174
	s_and_b64 vcc, exec, s[14:15]
	s_cbranch_vccz .LBB0_179
	s_barrier
	s_lshl_b32 s31, s8, 8
	s_cmp_gt_i32 s38, 1
	s_mov_b64 s[40:41], -1
	s_cbranch_scc1 .LBB0_180
